# G3a and G4 tile epilogues: second half's gate/residual loads issued as LDS-DMA together with the first half's loads (own dead B/A slots), read back with ds_read_b128; load-count waits of that half bec
# baseline (speedup 1.0000x reference)
; __device__ __forceinline__ unsigned pk2(float lo, float hi) { return pg8::cvt_pk_bf16(lo, hi); }
; __device__ __forceinline__ void unpack8(const u32x4 w, float (&f)[8]) { f[0] = bflo(w.x); f[1] = bfhi(w.x); f[2] = bflo(w.y); f[3] = bfhi(w.y); f[4] = bflo(w.z); f[5] = bfhi(w.z); f[6] = bflo(w.w); f[7] = bfhi(w.w); }
;     __device__ __forceinline__ void operator()(const f32x4 (&acc)[2][2][4][2], const Unit& u, int wr, int wc, int fr, int fq) const {
;         const int row0 = u.pm * 256 + wr * 64 + fr, col0 = u.pn * 256 + wc * 32 + 8 * fq;
; #pragma unroll
;         for (int ai = 0; ai < 2; ++ai) {
;             u32x4 graw[4][2], praw[4][2];
; #pragma unroll
;             for (int m = 0; m < 4; ++m)
; #pragma unroll
;                 for (int bj = 0; bj < 2; ++bj) { const int row = row0 + ai * 128 + m * 16; graw[m][bj] = *(const u32x4*)(Zg + (size_t)row * INC + col0 + bj * 128);
;                     if (SECOND) praw[m][bj] = *(const u32x4*)(O + (size_t)row * DM + col0 + bj * 128); }
;             __builtin_amdgcn_sched_barrier(0);
; #pragma unroll
;             for (int m = 0; m < 4; ++m) { const int row = row0 + ai * 128 + m * 16;
; #pragma unroll
;                 for (int bj = 0; bj < 2; ++bj) { const f32x4 a0 = acc[ai][bj][m][0], a1 = acc[ai][bj][m][1];
;                     float g[8]; unpack8(graw[m][bj], g);
;                     float v[8] = {g[0] * a0[0], g[1] * a0[1], g[2] * a0[2], g[3] * a0[3], g[4] * a1[0], g[5] * a1[1], g[6] * a1[2], g[7] * a1[3]};
;                     bf16_t* op = O + (size_t)row * DM + col0 + bj * 128;
;                     if (SECOND) { float p[8]; unpack8(praw[m][bj], p);
; #pragma unroll
;                         for (int k = 0; k < 8; ++k) v[k] += p[k]; }
;                     u32x4 w; w.x = pk2(v[0], v[1]); w.y = pk2(v[2], v[3]); w.z = pk2(v[4], v[5]); w.w = pk2(v[6], v[7]);
;                     *(u32x4*)op = w; } } }
.LBB0_679:
	v_lshl_or_b32 v156, s28, 8, v164
	v_ashrrev_i32_e32 v157, 31, v156
	v_readlane_b32 s0, v253, 58
	v_lshl_add_u32 v158, s29, 8, v162
	v_lshlrev_b64 v[156:157], 1, v[156:157]
	v_readlane_b32 s1, v253, 59
	v_or_b32_e32 v182, 16, v158
	v_or_b32_e32 v206, 32, v158
	v_lshl_add_u64 v[160:161], s[0:1], 0, v[156:157]
	v_or_b32_e32 v208, 48, v158
	v_mad_i64_i32 v[170:171], s[0:1], v158, s87, v[160:161]
	v_mad_i64_i32 v[178:179], s[0:1], v182, s87, v[160:161]
	v_mad_i64_i32 v[194:195], s[0:1], v206, s87, v[160:161]
	v_mad_i64_i32 v[202:203], s[0:1], v208, s87, v[160:161]
	global_load_dwordx4 v[166:169], v[170:171], off
	s_nop 0
	global_load_dwordx4 v[170:173], v[170:171], off offset:256
	s_nop 0
	global_load_dwordx4 v[174:177], v[178:179], off
	s_nop 0
	global_load_dwordx4 v[178:181], v[178:179], off offset:256
	s_nop 0
	global_load_dwordx4 v[190:193], v[194:195], off
	s_nop 0
	global_load_dwordx4 v[194:197], v[194:195], off offset:256
	s_nop 0
	global_load_dwordx4 v[198:201], v[202:203], off
	s_nop 0
	global_load_dwordx4 v[202:205], v[202:203], off offset:256
	s_cmp_lg_u64 s[6:7], 0
	s_cbranch_scc1 .Lhz_g3a_skip
	v_readfirstlane_b32 s98, v184
	s_lshr_b32 s98, s98, 6
	s_lshl_b32 s98, s98, 10
	v_mov_b32_e32 v230, 0x100
	v_mov_b32_e32 v231, 0
	v_add_u32_e32 v226, 0x80, v158
	v_mad_i64_i32 v[224:225], s[0:1], v226, s87, v[160:161]
	s_add_i32 m0, s98, 0x0
	s_nop 0
	global_load_lds_dwordx4 v[224:225], off
	v_lshl_add_u64 v[228:229], v[224:225], 0, v[230:231]
	s_add_i32 m0, s98, 0x2000
	s_nop 0
	global_load_lds_dwordx4 v[228:229], off
	v_add_u32_e32 v226, 0x90, v158
	v_mad_i64_i32 v[224:225], s[0:1], v226, s87, v[160:161]
	s_add_i32 m0, s98, 0x4000
	s_nop 0
	global_load_lds_dwordx4 v[224:225], off
	v_lshl_add_u64 v[228:229], v[224:225], 0, v[230:231]
	s_add_i32 m0, s98, 0x6000
	s_nop 0
	global_load_lds_dwordx4 v[228:229], off
	v_add_u32_e32 v226, 0xa0, v158
	v_mad_i64_i32 v[224:225], s[0:1], v226, s87, v[160:161]
	s_add_i32 m0, s98, 0x10000
	s_nop 0
	global_load_lds_dwordx4 v[224:225], off
	v_lshl_add_u64 v[228:229], v[224:225], 0, v[230:231]
	s_add_i32 m0, s98, 0x12000
	s_nop 0
	global_load_lds_dwordx4 v[228:229], off
	v_add_u32_e32 v226, 0xb0, v158
	v_mad_i64_i32 v[224:225], s[0:1], v226, s87, v[160:161]
	s_add_i32 m0, s98, 0x14000
	s_nop 0
	global_load_lds_dwordx4 v[224:225], off
	v_lshl_add_u64 v[228:229], v[224:225], 0, v[230:231]
	s_add_i32 m0, s98, 0x16000
	s_nop 0
	global_load_lds_dwordx4 v[228:229], off
.Lhz_g3a_skip:
	v_ashrrev_i32_e32 v159, 31, v158
	v_ashrrev_i32_e32 v183, 31, v182
	v_ashrrev_i32_e32 v207, 31, v206
	v_ashrrev_i32_e32 v209, 31, v208
	v_lshlrev_b64 v[220:221], 11, v[158:159]
	s_waitcnt vmcnt(0)
	v_lshlrev_b32_e32 v159, 16, v166
	v_and_b32_e32 v166, 0xffff0000, v166
	v_lshlrev_b32_e32 v186, 16, v167
	v_and_b32_e32 v167, 0xffff0000, v167
	v_lshlrev_b32_e32 v187, 16, v168
	v_and_b32_e32 v168, 0xffff0000, v168
	v_lshlrev_b32_e32 v210, 16, v169
	v_and_b32_e32 v169, 0xffff0000, v169
	v_mul_f32_e32 v166, v145, v166
	v_mul_f32_e32 v147, v147, v167
	v_mul_f32_e32 v167, v140, v187
	v_mul_f32_e32 v168, v141, v168
	v_mul_f32_e32 v143, v143, v169
	v_lshl_add_u64 v[140:141], s[68:69], 0, v[220:221]
	v_mul_f32_e32 v159, v144, v159
	v_mul_f32_e32 v146, v146, v186
	v_mul_f32_e32 v186, v142, v210
	v_lshl_add_u64 v[144:145], v[140:141], 0, v[156:157]
	v_cvt_pk_bf16_f32 v140, v159, v166
	v_cvt_pk_bf16_f32 v141, v146, v147
	v_cvt_pk_bf16_f32 v142, v167, v168
	v_cvt_pk_bf16_f32 v143, v186, v143
	v_and_b32_e32 v166, 0xffff0000, v173
	global_store_dwordx4 v[144:145], v[140:143], off
	v_lshlrev_b32_e32 v146, 16, v172
	v_and_b32_e32 v147, 0xffff0000, v172
	v_lshlrev_b32_e32 v140, 16, v170
	v_and_b32_e32 v141, 0xffff0000, v170
	v_lshlrev_b32_e32 v142, 16, v171
	v_and_b32_e32 v143, 0xffff0000, v171
	v_lshlrev_b32_e32 v159, 16, v173
	v_mul_f32_e32 v131, v131, v166
	v_mul_f32_e32 v136, v136, v140
	v_mul_f32_e32 v137, v137, v141
	v_mul_f32_e32 v138, v138, v142
	v_mul_f32_e32 v139, v139, v143
	v_mul_f32_e32 v140, v128, v146
	v_mul_f32_e32 v141, v129, v147
	v_mul_f32_e32 v142, v130, v159
	v_cvt_pk_bf16_f32 v128, v136, v137
	v_cvt_pk_bf16_f32 v129, v138, v139
	v_cvt_pk_bf16_f32 v130, v140, v141
	v_cvt_pk_bf16_f32 v131, v142, v131
	global_store_dwordx4 v[144:145], v[128:131], off offset:256
	v_lshlrev_b32_e32 v136, 16, v175
	v_and_b32_e32 v137, 0xffff0000, v175
	v_lshlrev_b64 v[128:129], 11, v[182:183]
	v_lshlrev_b32_e32 v130, 16, v174
	v_and_b32_e32 v131, 0xffff0000, v174
	v_lshlrev_b32_e32 v138, 16, v176
	v_and_b32_e32 v139, 0xffff0000, v176
	v_and_b32_e32 v141, 0xffff0000, v177
	v_lshlrev_b32_e32 v140, 16, v177
	v_mul_f32_e32 v130, v132, v130
	v_mul_f32_e32 v131, v133, v131
	v_mul_f32_e32 v132, v134, v136
	v_mul_f32_e32 v133, v135, v137
	v_mul_f32_e32 v134, v124, v138
	v_mul_f32_e32 v135, v125, v139
	v_mul_f32_e32 v127, v127, v141
	v_lshl_add_u64 v[124:125], s[68:69], 0, v[128:129]
	v_mul_f32_e32 v136, v126, v140
	v_lshl_add_u64 v[128:129], v[124:125], 0, v[156:157]
	v_cvt_pk_bf16_f32 v124, v130, v131
	v_cvt_pk_bf16_f32 v125, v132, v133
	v_cvt_pk_bf16_f32 v126, v134, v135
	v_cvt_pk_bf16_f32 v127, v136, v127
	v_and_b32_e32 v133, 0xffff0000, v181
	global_store_dwordx4 v[128:129], v[124:127], off
	v_lshlrev_b32_e32 v130, 16, v180
	v_and_b32_e32 v131, 0xffff0000, v180
	v_lshlrev_b32_e32 v124, 16, v178
	v_and_b32_e32 v125, 0xffff0000, v178
	v_lshlrev_b32_e32 v126, 16, v179
	v_and_b32_e32 v127, 0xffff0000, v179
	v_lshlrev_b32_e32 v132, 16, v181
	v_mul_f32_e32 v115, v115, v133
	v_mul_f32_e32 v120, v120, v124
	v_mul_f32_e32 v121, v121, v125
	v_mul_f32_e32 v122, v122, v126
	v_mul_f32_e32 v123, v123, v127
	v_mul_f32_e32 v124, v112, v130
	v_mul_f32_e32 v125, v113, v131
; __device__ __forceinline__ unsigned pk2(float lo, float hi) { return pg8::cvt_pk_bf16(lo, hi); }
; __device__ __forceinline__ void unpack8(const u32x4 w, float (&f)[8]) { f[0] = bflo(w.x); f[1] = bfhi(w.x); f[2] = bflo(w.y); f[3] = bfhi(w.y); f[4] = bflo(w.z); f[5] = bfhi(w.z); f[6] = bflo(w.w); f[7] = bfhi(w.w); }
;     __device__ __forceinline__ void operator()(const f32x4 (&acc)[2][2][4][2], const Unit& u, int wr, int wc, int fr, int fq) const {
;         const int row0 = u.pm * 256 + wr * 64 + fr, col0 = u.pn * 256 + wc * 32 + 8 * fq;
; #pragma unroll
;         for (int ai = 0; ai < 2; ++ai) {
;             u32x4 graw[4][2], praw[4][2];
; #pragma unroll
;             for (int m = 0; m < 4; ++m)
; #pragma unroll
;                 for (int bj = 0; bj < 2; ++bj) { const int row = row0 + ai * 128 + m * 16; graw[m][bj] = *(const u32x4*)(Zg + (size_t)row * INC + col0 + bj * 128);
;                     if (SECOND) praw[m][bj] = *(const u32x4*)(O + (size_t)row * DM + col0 + bj * 128); }
;             __builtin_amdgcn_sched_barrier(0);
; #pragma unroll
;             for (int m = 0; m < 4; ++m) { const int row = row0 + ai * 128 + m * 16;
; #pragma unroll
;                 for (int bj = 0; bj < 2; ++bj) { const f32x4 a0 = acc[ai][bj][m][0], a1 = acc[ai][bj][m][1];
;                     float g[8]; unpack8(graw[m][bj], g);
;                     float v[8] = {g[0] * a0[0], g[1] * a0[1], g[2] * a0[2], g[3] * a0[3], g[4] * a1[0], g[5] * a1[1], g[6] * a1[2], g[7] * a1[3]};
;                     bf16_t* op = O + (size_t)row * DM + col0 + bj * 128;
;                     if (SECOND) { float p[8]; unpack8(praw[m][bj], p);
; #pragma unroll
;                         for (int k = 0; k < 8; ++k) v[k] += p[k]; }
;                     u32x4 w; w.x = pk2(v[0], v[1]); w.y = pk2(v[2], v[3]); w.z = pk2(v[4], v[5]); w.w = pk2(v[6], v[7]);
;                     *(u32x4*)op = w; } } }
	v_mul_f32_e32 v126, v114, v132
	v_cvt_pk_bf16_f32 v112, v120, v121
	v_cvt_pk_bf16_f32 v113, v122, v123
	v_cvt_pk_bf16_f32 v114, v124, v125
	v_cvt_pk_bf16_f32 v115, v126, v115
	global_store_dwordx4 v[128:129], v[112:115], off offset:256
	v_lshlrev_b32_e32 v120, 16, v191
	v_and_b32_e32 v121, 0xffff0000, v191
	v_lshlrev_b64 v[112:113], 11, v[206:207]
	v_lshlrev_b32_e32 v114, 16, v190
	v_and_b32_e32 v115, 0xffff0000, v190
	v_lshlrev_b32_e32 v122, 16, v192
	v_and_b32_e32 v123, 0xffff0000, v192
	v_and_b32_e32 v125, 0xffff0000, v193
	v_lshlrev_b32_e32 v124, 16, v193
	v_mul_f32_e32 v114, v116, v114
	v_mul_f32_e32 v115, v117, v115
	v_mul_f32_e32 v116, v118, v120
	v_mul_f32_e32 v117, v119, v121
	v_mul_f32_e32 v118, v108, v122
	v_mul_f32_e32 v119, v109, v123
	v_mul_f32_e32 v111, v111, v125
	v_lshl_add_u64 v[108:109], s[68:69], 0, v[112:113]
	v_mul_f32_e32 v120, v110, v124
	v_lshl_add_u64 v[112:113], v[108:109], 0, v[156:157]
	v_cvt_pk_bf16_f32 v108, v114, v115
	v_cvt_pk_bf16_f32 v109, v116, v117
	v_cvt_pk_bf16_f32 v110, v118, v119
	v_cvt_pk_bf16_f32 v111, v120, v111
	v_and_b32_e32 v117, 0xffff0000, v197
	global_store_dwordx4 v[112:113], v[108:111], off
	v_lshlrev_b32_e32 v114, 16, v196
	v_and_b32_e32 v115, 0xffff0000, v196
	v_lshlrev_b32_e32 v108, 16, v194
	v_and_b32_e32 v109, 0xffff0000, v194
	v_lshlrev_b32_e32 v110, 16, v195
	v_and_b32_e32 v111, 0xffff0000, v195
	v_lshlrev_b32_e32 v116, 16, v197
	v_mul_f32_e32 v99, v99, v117
	v_mul_f32_e32 v104, v104, v108
	v_mul_f32_e32 v105, v105, v109
	v_mul_f32_e32 v106, v106, v110
	v_mul_f32_e32 v107, v107, v111
	v_mul_f32_e32 v108, v96, v114
	v_mul_f32_e32 v109, v97, v115
	v_mul_f32_e32 v110, v98, v116
	v_cvt_pk_bf16_f32 v96, v104, v105
	v_cvt_pk_bf16_f32 v97, v106, v107
	v_cvt_pk_bf16_f32 v98, v108, v109
	v_cvt_pk_bf16_f32 v99, v110, v99
	global_store_dwordx4 v[112:113], v[96:99], off offset:256
	v_lshlrev_b32_e32 v104, 16, v199
	v_and_b32_e32 v105, 0xffff0000, v199
	v_lshlrev_b64 v[96:97], 11, v[208:209]
	v_lshlrev_b32_e32 v98, 16, v198
	v_and_b32_e32 v99, 0xffff0000, v198
	v_lshlrev_b32_e32 v106, 16, v200
	v_and_b32_e32 v107, 0xffff0000, v200
	v_and_b32_e32 v109, 0xffff0000, v201
	v_mul_f32_e32 v98, v100, v98
	v_mul_f32_e32 v99, v101, v99
	v_mul_f32_e32 v100, v102, v104
	v_mul_f32_e32 v101, v103, v105
	v_mul_f32_e32 v102, v92, v106
	v_mul_f32_e32 v103, v93, v107
	v_lshl_add_u64 v[92:93], s[68:69], 0, v[96:97]
	v_lshlrev_b32_e32 v108, 16, v201
	v_mul_f32_e32 v95, v95, v109
	v_lshl_add_u64 v[96:97], v[92:93], 0, v[156:157]
	v_cvt_pk_bf16_f32 v92, v98, v99
	v_cvt_pk_bf16_f32 v93, v100, v101
	v_mul_f32_e32 v104, v94, v108
	v_cvt_pk_bf16_f32 v94, v102, v103
	v_cvt_pk_bf16_f32 v95, v104, v95
	global_store_dwordx4 v[96:97], v[92:95], off
	v_and_b32_e32 v101, 0xffff0000, v205
	v_lshlrev_b32_e32 v98, 16, v204
	v_lshlrev_b32_e32 v92, 16, v202
	v_and_b32_e32 v93, 0xffff0000, v202
	v_lshlrev_b32_e32 v94, 16, v203
	v_and_b32_e32 v95, 0xffff0000, v203
	v_and_b32_e32 v99, 0xffff0000, v204
	v_lshlrev_b32_e32 v100, 16, v205
	v_mul_f32_e32 v88, v88, v92
	v_mul_f32_e32 v89, v89, v93
	v_mul_f32_e32 v87, v87, v101
	v_add_u32_e32 v116, 0x80, v158
	v_add_u32_e32 v118, 0x90, v158
	v_add_u32_e32 v120, 0xa0, v158
	v_add_u32_e32 v122, 0xb0, v158
	v_mul_f32_e32 v90, v90, v94
	v_mul_f32_e32 v91, v91, v95
	v_mul_f32_e32 v92, v84, v98
	v_mul_f32_e32 v93, v85, v99
	v_mul_f32_e32 v94, v86, v100
	v_cvt_pk_bf16_f32 v84, v88, v89
	v_cvt_pk_bf16_f32 v85, v90, v91
	v_cvt_pk_bf16_f32 v86, v92, v93
	v_cvt_pk_bf16_f32 v87, v94, v87
	global_store_dwordx4 v[96:97], v[84:87], off offset:256
	v_mad_i64_i32 v[88:89], s[0:1], v116, s87, v[160:161]
	v_mad_i64_i32 v[96:97], s[0:1], v118, s87, v[160:161]
	v_mad_i64_i32 v[104:105], s[0:1], v120, s87, v[160:161]
	v_mad_i64_i32 v[112:113], s[0:1], v122, s87, v[160:161]
	s_cmp_lg_u64 s[6:7], 0
	s_cbranch_scc0 .Lhz_g3a_lds
	global_load_dwordx4 v[84:87], v[88:89], off
	s_nop 0
	global_load_dwordx4 v[88:91], v[88:89], off offset:256
	s_nop 0
	global_load_dwordx4 v[92:95], v[96:97], off
	s_nop 0
	global_load_dwordx4 v[96:99], v[96:97], off offset:256
	s_nop 0
	global_load_dwordx4 v[100:103], v[104:105], off
	s_nop 0
	global_load_dwordx4 v[104:107], v[104:105], off offset:256
	s_nop 0
	global_load_dwordx4 v[108:111], v[112:113], off
	s_nop 0
	global_load_dwordx4 v[112:115], v[112:113], off offset:256
	s_waitcnt vmcnt(0)
	s_branch .Lhz_g3a_join
.Lhz_g3a_lds:
	v_readfirstlane_b32 s98, v184
	s_lshr_b32 s98, s98, 6
	s_lshl_b32 s98, s98, 10
	v_and_b32_e32 v226, 63, v184
	v_lshl_add_u32 v226, v226, 4, s98
	v_add_u32_e32 v227, 0x10000, v226
	ds_read_b128 v[84:87], v226 offset:0
	ds_read_b128 v[88:91], v226 offset:8192
	ds_read_b128 v[92:95], v226 offset:16384
	ds_read_b128 v[96:99], v226 offset:24576
	ds_read_b128 v[100:103], v227 offset:0
	ds_read_b128 v[104:107], v227 offset:8192
	ds_read_b128 v[108:111], v227 offset:16384
	ds_read_b128 v[112:115], v227 offset:24576
	s_waitcnt lgkmcnt(0)
; __device__ __forceinline__ unsigned pk2(float lo, float hi) { return pg8::cvt_pk_bf16(lo, hi); }
; __device__ __forceinline__ void unpack8(const u32x4 w, float (&f)[8]) { f[0] = bflo(w.x); f[1] = bfhi(w.x); f[2] = bflo(w.y); f[3] = bfhi(w.y); f[4] = bflo(w.z); f[5] = bfhi(w.z); f[6] = bflo(w.w); f[7] = bfhi(w.w); }
;     __device__ __forceinline__ void operator()(const f32x4 (&acc)[2][2][4][2], const Unit& u, int wr, int wc, int fr, int fq) const {
;         const int row0 = u.pm * 256 + wr * 64 + fr, col0 = u.pn * 256 + wc * 32 + 8 * fq;
; #pragma unroll
;         for (int ai = 0; ai < 2; ++ai) {
;             u32x4 graw[4][2], praw[4][2];
; #pragma unroll
;             for (int m = 0; m < 4; ++m)
; #pragma unroll
;                 for (int bj = 0; bj < 2; ++bj) { const int row = row0 + ai * 128 + m * 16; graw[m][bj] = *(const u32x4*)(Zg + (size_t)row * INC + col0 + bj * 128);
;                     if (SECOND) praw[m][bj] = *(const u32x4*)(O + (size_t)row * DM + col0 + bj * 128); }
;             __builtin_amdgcn_sched_barrier(0);
; #pragma unroll
;             for (int m = 0; m < 4; ++m) { const int row = row0 + ai * 128 + m * 16;
; #pragma unroll
;                 for (int bj = 0; bj < 2; ++bj) { const f32x4 a0 = acc[ai][bj][m][0], a1 = acc[ai][bj][m][1];
;                     float g[8]; unpack8(graw[m][bj], g);
;                     float v[8] = {g[0] * a0[0], g[1] * a0[1], g[2] * a0[2], g[3] * a0[3], g[4] * a1[0], g[5] * a1[1], g[6] * a1[2], g[7] * a1[3]};
;                     bf16_t* op = O + (size_t)row * DM + col0 + bj * 128;
;                     if (SECOND) { float p[8]; unpack8(praw[m][bj], p);
; #pragma unroll
;                         for (int k = 0; k < 8; ++k) v[k] += p[k]; }
;                     u32x4 w; w.x = pk2(v[0], v[1]); w.y = pk2(v[2], v[3]); w.z = pk2(v[4], v[5]); w.w = pk2(v[6], v[7]);
;                     *(u32x4*)op = w; } } }
.Lhz_g3a_join:
	v_ashrrev_i32_e32 v117, 31, v116
	v_ashrrev_i32_e32 v119, 31, v118
	v_ashrrev_i32_e32 v121, 31, v120
	v_ashrrev_i32_e32 v123, 31, v122
	v_lshlrev_b64 v[116:117], 11, v[116:117]
	s_nop 0
	v_lshlrev_b32_e32 v125, 16, v85
	v_and_b32_e32 v85, 0xffff0000, v85
	v_lshlrev_b32_e32 v126, 16, v86
	v_and_b32_e32 v86, 0xffff0000, v86
	v_lshlrev_b32_e32 v127, 16, v87
	v_and_b32_e32 v87, 0xffff0000, v87
	v_lshlrev_b32_e32 v124, 16, v84
	v_and_b32_e32 v84, 0xffff0000, v84
	v_mul_f32_e32 v83, v83, v85
	v_mul_f32_e32 v85, v76, v126
	v_mul_f32_e32 v86, v77, v86
	v_mul_f32_e32 v79, v79, v87
	v_lshl_add_u64 v[76:77], s[68:69], 0, v[116:117]
	v_mul_f32_e32 v124, v80, v124
	v_mul_f32_e32 v84, v81, v84
	v_mul_f32_e32 v82, v82, v125
	v_mul_f32_e32 v125, v78, v127
	v_lshl_add_u64 v[80:81], v[76:77], 0, v[156:157]
	v_cvt_pk_bf16_f32 v76, v124, v84
	v_cvt_pk_bf16_f32 v77, v82, v83
	v_cvt_pk_bf16_f32 v78, v85, v86
	v_cvt_pk_bf16_f32 v79, v125, v79
	s_nop 0
	v_and_b32_e32 v85, 0xffff0000, v91
	global_store_dwordx4 v[80:81], v[76:79], off
	v_lshlrev_b32_e32 v82, 16, v90
	v_and_b32_e32 v83, 0xffff0000, v90
	v_lshlrev_b32_e32 v76, 16, v88
	v_and_b32_e32 v77, 0xffff0000, v88
	v_lshlrev_b32_e32 v78, 16, v89
	v_and_b32_e32 v79, 0xffff0000, v89
	v_lshlrev_b32_e32 v84, 16, v91
	v_mul_f32_e32 v67, v67, v85
	v_mul_f32_e32 v72, v72, v76
	v_mul_f32_e32 v73, v73, v77
	v_mul_f32_e32 v74, v74, v78
	v_mul_f32_e32 v75, v75, v79
	v_mul_f32_e32 v76, v64, v82
	v_mul_f32_e32 v77, v65, v83
	v_mul_f32_e32 v78, v66, v84
	v_cvt_pk_bf16_f32 v64, v72, v73
	v_cvt_pk_bf16_f32 v65, v74, v75
	v_cvt_pk_bf16_f32 v66, v76, v77
	v_cvt_pk_bf16_f32 v67, v78, v67
	global_store_dwordx4 v[80:81], v[64:67], off offset:256
	s_nop 0
	v_lshlrev_b32_e32 v72, 16, v93
	v_and_b32_e32 v73, 0xffff0000, v93
	v_lshlrev_b64 v[64:65], 11, v[118:119]
	v_lshlrev_b32_e32 v66, 16, v92
	v_and_b32_e32 v67, 0xffff0000, v92
	v_lshlrev_b32_e32 v74, 16, v94
	v_and_b32_e32 v75, 0xffff0000, v94
	v_and_b32_e32 v77, 0xffff0000, v95
	v_lshlrev_b32_e32 v76, 16, v95
	v_mul_f32_e32 v66, v68, v66
	v_mul_f32_e32 v67, v69, v67
	v_mul_f32_e32 v68, v70, v72
	v_mul_f32_e32 v69, v71, v73
	v_mul_f32_e32 v70, v60, v74
	v_mul_f32_e32 v71, v61, v75
	v_mul_f32_e32 v63, v63, v77
	v_lshl_add_u64 v[60:61], s[68:69], 0, v[64:65]
	v_mul_f32_e32 v72, v62, v76
	v_lshl_add_u64 v[64:65], v[60:61], 0, v[156:157]
	v_cvt_pk_bf16_f32 v60, v66, v67
	v_cvt_pk_bf16_f32 v61, v68, v69
	v_cvt_pk_bf16_f32 v62, v70, v71
	v_cvt_pk_bf16_f32 v63, v72, v63
	s_nop 0
	v_and_b32_e32 v69, 0xffff0000, v99
	global_store_dwordx4 v[64:65], v[60:63], off
	v_lshlrev_b32_e32 v66, 16, v98
	v_and_b32_e32 v67, 0xffff0000, v98
	v_lshlrev_b32_e32 v60, 16, v96
	v_and_b32_e32 v61, 0xffff0000, v96
	v_lshlrev_b32_e32 v62, 16, v97
	v_and_b32_e32 v63, 0xffff0000, v97
	v_lshlrev_b32_e32 v68, 16, v99
	v_mul_f32_e32 v51, v51, v69
	v_mul_f32_e32 v56, v56, v60
	v_mul_f32_e32 v57, v57, v61
	v_mul_f32_e32 v58, v58, v62
	v_mul_f32_e32 v59, v59, v63
	v_mul_f32_e32 v60, v48, v66
	v_mul_f32_e32 v61, v49, v67
	v_mul_f32_e32 v62, v50, v68
	v_cvt_pk_bf16_f32 v48, v56, v57
	v_cvt_pk_bf16_f32 v49, v58, v59
	v_cvt_pk_bf16_f32 v50, v60, v61
	v_cvt_pk_bf16_f32 v51, v62, v51
	global_store_dwordx4 v[64:65], v[48:51], off offset:256
	s_nop 0
	v_lshlrev_b32_e32 v56, 16, v101
	v_and_b32_e32 v57, 0xffff0000, v101
	v_lshlrev_b64 v[48:49], 11, v[120:121]
	v_lshlrev_b32_e32 v50, 16, v100
	v_and_b32_e32 v51, 0xffff0000, v100
	v_lshlrev_b32_e32 v58, 16, v102
	v_and_b32_e32 v59, 0xffff0000, v102
	v_and_b32_e32 v61, 0xffff0000, v103
	v_lshlrev_b32_e32 v60, 16, v103
	v_mul_f32_e32 v50, v52, v50
	v_mul_f32_e32 v51, v53, v51
	v_mul_f32_e32 v52, v54, v56
	v_mul_f32_e32 v53, v55, v57
	v_mul_f32_e32 v54, v44, v58
	v_mul_f32_e32 v55, v45, v59
	v_mul_f32_e32 v47, v47, v61
	v_lshl_add_u64 v[44:45], s[68:69], 0, v[48:49]
	v_mul_f32_e32 v56, v46, v60
	v_lshl_add_u64 v[48:49], v[44:45], 0, v[156:157]
	v_cvt_pk_bf16_f32 v44, v50, v51
	v_cvt_pk_bf16_f32 v45, v52, v53
	v_cvt_pk_bf16_f32 v46, v54, v55
	v_cvt_pk_bf16_f32 v47, v56, v47
	s_nop 0
	v_and_b32_e32 v53, 0xffff0000, v107
	global_store_dwordx4 v[48:49], v[44:47], off
	v_lshlrev_b32_e32 v50, 16, v106
	v_and_b32_e32 v51, 0xffff0000, v106
	v_lshlrev_b32_e32 v44, 16, v104
	v_and_b32_e32 v45, 0xffff0000, v104
	v_lshlrev_b32_e32 v46, 16, v105
	v_and_b32_e32 v47, 0xffff0000, v105
	v_lshlrev_b32_e32 v52, 16, v107
	v_mul_f32_e32 v35, v35, v53
	v_mul_f32_e32 v40, v40, v44
	v_mul_f32_e32 v41, v41, v45
	v_mul_f32_e32 v42, v42, v46
	v_mul_f32_e32 v43, v43, v47
	v_mul_f32_e32 v44, v32, v50
	v_mul_f32_e32 v45, v33, v51
	v_mul_f32_e32 v46, v34, v52
	v_cvt_pk_bf16_f32 v32, v40, v41
	v_cvt_pk_bf16_f32 v33, v42, v43
	v_cvt_pk_bf16_f32 v34, v44, v45
	v_cvt_pk_bf16_f32 v35, v46, v35
	global_store_dwordx4 v[48:49], v[32:35], off offset:256
	s_nop 0
	v_lshlrev_b32_e32 v40, 16, v109
	v_and_b32_e32 v41, 0xffff0000, v109
	v_lshlrev_b64 v[32:33], 11, v[122:123]
	v_lshlrev_b32_e32 v34, 16, v108
	v_and_b32_e32 v35, 0xffff0000, v108
	v_lshlrev_b32_e32 v42, 16, v110
	v_and_b32_e32 v43, 0xffff0000, v110
	v_and_b32_e32 v45, 0xffff0000, v111
	v_lshlrev_b32_e32 v44, 16, v111
	v_mul_f32_e32 v34, v36, v34
	v_mul_f32_e32 v35, v37, v35
	v_mul_f32_e32 v36, v38, v40
	v_mul_f32_e32 v37, v39, v41
	v_mul_f32_e32 v38, v28, v42
	v_mul_f32_e32 v39, v29, v43
	v_mul_f32_e32 v31, v31, v45
	v_lshl_add_u64 v[28:29], s[68:69], 0, v[32:33]
	v_mul_f32_e32 v40, v30, v44
	v_lshl_add_u64 v[32:33], v[28:29], 0, v[156:157]
	v_cvt_pk_bf16_f32 v28, v34, v35
	v_cvt_pk_bf16_f32 v29, v36, v37
	v_cvt_pk_bf16_f32 v30, v38, v39
	v_cvt_pk_bf16_f32 v31, v40, v31
	s_nop 0
	v_and_b32_e32 v37, 0xffff0000, v115
	global_store_dwordx4 v[32:33], v[28:31], off
	v_lshlrev_b32_e32 v34, 16, v114
	v_and_b32_e32 v35, 0xffff0000, v114
	v_lshlrev_b32_e32 v28, 16, v112
	v_and_b32_e32 v29, 0xffff0000, v112
	v_lshlrev_b32_e32 v30, 16, v113
	v_and_b32_e32 v31, 0xffff0000, v113
	v_lshlrev_b32_e32 v36, 16, v115
	v_mul_f32_e32 v23, v23, v37
	s_andn2_b64 vcc, exec, s[6:7]
	s_mov_b64 s[0:1], -1
	s_mov_b32 s35, 0x18000
	s_mov_b32 s72, 0xc000
	v_mul_f32_e32 v24, v24, v28
	v_mul_f32_e32 v25, v25, v29
	v_mul_f32_e32 v26, v26, v30
	v_mul_f32_e32 v27, v27, v31
	v_mul_f32_e32 v28, v20, v34
	v_mul_f32_e32 v29, v21, v35
	v_mul_f32_e32 v30, v22, v36
	v_cvt_pk_bf16_f32 v20, v24, v25
	v_cvt_pk_bf16_f32 v21, v26, v27
	v_cvt_pk_bf16_f32 v22, v28, v29
	v_cvt_pk_bf16_f32 v23, v30, v23
	global_store_dwordx4 v[32:33], v[20:23], off offset:256
	s_cbranch_vccnz .LBB0_668
	s_andn2_b64 vcc, exec, s[4:5]
	s_cbranch_vccnz .LBB0_667
	s_barrier
	s_branch .LBB0_667

; __device__ __forceinline__ unsigned pk2(float lo, float hi) { return pg8::cvt_pk_bf16(lo, hi); }
; __device__ __forceinline__ void unpack8(const u32x4 w, float (&f)[8]) { f[0] = bflo(w.x); f[1] = bfhi(w.x); f[2] = bflo(w.y); f[3] = bfhi(w.y); f[4] = bflo(w.z); f[5] = bfhi(w.z); f[6] = bflo(w.w); f[7] = bfhi(w.w); }
;     __device__ __forceinline__ void operator()(const f32x4 (&acc)[2][2][4][2], const Unit& u, int wr, int wc, int fr, int fq) const {
;         const int row0 = u.pm * 256 + wr * 64 + fr, col0 = u.pn * 256 + wc * 32 + 8 * fq;
; #pragma unroll
;         for (int ai = 0; ai < 2; ++ai) {
;             u32x4 braw[4][2];
; #pragma unroll
;             for (int m = 0; m < 4; ++m)
; #pragma unroll
;                 for (int bj = 0; bj < 2; ++bj) braw[m][bj] = *(const u32x4*)(base + (size_t)(row0 + ai * 128 + m * 16) * DM + col0 + bj * 128);
;             __builtin_amdgcn_sched_barrier(0);
; #pragma unroll
;             for (int m = 0; m < 4; ++m) { const int row = row0 + ai * 128 + m * 16; const size_t off = (size_t)row * DM + col0; float sq = 0.f;
; #pragma unroll
;                 for (int bj = 0; bj < 2; ++bj) { float b[8]; unpack8(braw[m][bj], b);
;                     const f32x4 a0 = acc[ai][bj][m][0], a1 = acc[ai][bj][m][1];
;                     const f32x4 v0 = (f32x4){b[0] + a0[0], b[1] + a0[1], b[2] + a0[2], b[3] + a0[3]}, v1 = (f32x4){b[4] + a1[0], b[5] + a1[1], b[6] + a1[2], b[7] + a1[3]};
;                     sq += (v0[0] * v0[0] + v0[1] * v0[1]) + (v0[2] * v0[2] + v0[3] * v0[3]) + (v1[0] * v1[0] + v1[1] * v1[1]) + (v1[2] * v1[2] + v1[3] * v1[3]);
;                     if (Xf) { *(f32x4*)(Xf + off + bj * 128) = v0; *(f32x4*)(Xf + off + bj * 128 + 4) = v1; }
;                     if (XB) { u32x4 w; w.x = pk2(v0[0], v0[1]); w.y = pk2(v0[2], v0[3]); w.z = pk2(v1[0], v1[1]); w.w = pk2(v1[2], v1[3]); *(u32x4*)(XB + off + bj * 128) = w; } }
;                 if (ss) { sq += __shfl_xor(sq, 16); sq += __shfl_xor(sq, 32); if (fq == 0) atomicAdd(ss + row, sq); } } }
.LBB0_777:
	v_lshl_or_b32 v180, s28, 8, v206
	v_lshl_add_u32 v182, s29, 8, v204
	v_ashrrev_i32_e32 v181, 31, v180
	v_lshlrev_b64 v[186:187], 1, v[180:181]
	v_ashrrev_i32_e32 v183, 31, v182
	v_or_b32_e32 v200, 16, v182
	v_lshl_add_u64 v[190:191], s[30:31], 0, v[186:187]
	v_lshlrev_b64 v[208:209], 11, v[182:183]
	v_ashrrev_i32_e32 v201, 31, v200
	v_or_b32_e32 v196, 32, v182
	v_lshl_add_u64 v[148:149], v[190:191], 0, v[208:209]
	v_lshlrev_b64 v[202:203], 11, v[200:201]
	v_ashrrev_i32_e32 v197, 31, v196
	v_or_b32_e32 v192, 48, v182
	global_load_dwordx4 v[220:223], v[148:149], off
	global_load_dwordx4 v[224:227], v[148:149], off offset:256
	v_lshl_add_u64 v[148:149], v[190:191], 0, v[202:203]
	v_lshlrev_b64 v[198:199], 11, v[196:197]
	v_ashrrev_i32_e32 v193, 31, v192
	global_load_dwordx4 v[168:171], v[148:149], off
	global_load_dwordx4 v[164:167], v[148:149], off offset:256
	v_lshl_add_u64 v[148:149], v[190:191], 0, v[198:199]
	v_lshlrev_b64 v[194:195], 11, v[192:193]
	global_load_dwordx4 v[160:163], v[148:149], off
	global_load_dwordx4 v[156:159], v[148:149], off offset:256
	v_lshl_add_u64 v[148:149], v[190:191], 0, v[194:195]
	global_load_dwordx4 v[152:155], v[148:149], off
	s_nop 0
	global_load_dwordx4 v[148:151], v[148:149], off offset:256
	s_cmp_lg_u64 s[10:11], 0
	s_cbranch_scc1 .Lhz_g4_skip
	v_readfirstlane_b32 s98, v184
	s_lshr_b32 s98, s98, 6
	s_lshl_b32 s98, s98, 10
	v_mov_b32_e32 v246, 0x100
	v_mov_b32_e32 v247, 0
	v_add_u32_e32 v240, 0x80, v182
	v_lshlrev_b32_e32 v240, 11, v240
	v_mov_b32_e32 v241, 0
	v_lshl_add_u64 v[242:243], v[240:241], 0, v[190:191]
	s_add_i32 m0, s98, 0x0
	s_nop 0
	global_load_lds_dwordx4 v[242:243], off
	v_lshl_add_u64 v[244:245], v[242:243], 0, v[246:247]
	s_add_i32 m0, s98, 0x2000
	s_nop 0
	global_load_lds_dwordx4 v[244:245], off
	v_add_u32_e32 v240, 0x90, v182
	v_lshlrev_b32_e32 v240, 11, v240
	v_mov_b32_e32 v241, 0
	v_lshl_add_u64 v[242:243], v[240:241], 0, v[190:191]
	s_add_i32 m0, s98, 0x4000
	s_nop 0
	global_load_lds_dwordx4 v[242:243], off
	v_lshl_add_u64 v[244:245], v[242:243], 0, v[246:247]
	s_add_i32 m0, s98, 0x6000
	s_nop 0
	global_load_lds_dwordx4 v[244:245], off
	v_add_u32_e32 v240, 0xa0, v182
	v_lshlrev_b32_e32 v240, 11, v240
	v_mov_b32_e32 v241, 0
	v_lshl_add_u64 v[242:243], v[240:241], 0, v[190:191]
	s_add_i32 m0, s98, 0x10000
	s_nop 0
	global_load_lds_dwordx4 v[242:243], off
	v_lshl_add_u64 v[244:245], v[242:243], 0, v[246:247]
	s_add_i32 m0, s98, 0x12000
	s_nop 0
	global_load_lds_dwordx4 v[244:245], off
	v_add_u32_e32 v240, 0xb0, v182
	v_lshlrev_b32_e32 v240, 11, v240
	v_mov_b32_e32 v241, 0
	v_lshl_add_u64 v[242:243], v[240:241], 0, v[190:191]
	s_add_i32 m0, s98, 0x14000
	s_nop 0
	global_load_lds_dwordx4 v[242:243], off
	v_lshl_add_u64 v[244:245], v[242:243], 0, v[246:247]
	s_add_i32 m0, s98, 0x16000
	s_nop 0
	global_load_lds_dwordx4 v[244:245], off
.Lhz_g4_skip:
	s_waitcnt vmcnt(0)
	v_and_b32_e32 v189, 0xffff0000, v220
	v_and_b32_e32 v211, 0xffff0000, v221
	v_lshlrev_b32_e32 v188, 16, v220
	v_lshlrev_b32_e32 v210, 16, v221
	v_lshlrev_b32_e32 v212, 16, v222
	v_and_b32_e32 v213, 0xffff0000, v222
	v_add_f32_e32 v145, v145, v189
	v_add_f32_e32 v147, v147, v211
	v_add_f32_e32 v144, v144, v188
	v_add_f32_e32 v146, v146, v210
	v_add_f32_e32 v188, v140, v212
	v_add_f32_e32 v189, v141, v213
	v_mul_f32_e32 v140, v145, v145
	v_mul_f32_e32 v141, v147, v147
	v_fmac_f32_e32 v140, v144, v144
	v_fmac_f32_e32 v141, v146, v146
	v_and_b32_e32 v218, 0xffff0000, v223
	v_add_f32_e32 v140, v140, v141
	v_mul_f32_e32 v141, v189, v189
	v_lshlrev_b32_e32 v217, 16, v223
	v_add_f32_e32 v143, v143, v218
	v_fmac_f32_e32 v141, v188, v188
	v_add_f32_e32 v210, v142, v217
	v_add_f32_e32 v140, v141, v140
	v_mul_f32_e32 v141, v143, v143
	v_fmac_f32_e32 v141, v210, v210
	v_add_f32_e32 v211, v141, v140
	v_cvt_pk_bf16_f32 v140, v144, v145
	v_cvt_pk_bf16_f32 v141, v146, v147
	v_and_b32_e32 v145, 0xffff0000, v224
	v_and_b32_e32 v147, 0xffff0000, v225
	v_cvt_pk_bf16_f32 v142, v188, v189
	v_lshlrev_b32_e32 v144, 16, v224
	v_lshlrev_b32_e32 v146, 16, v225
	v_lshlrev_b32_e32 v188, 16, v226
	v_and_b32_e32 v189, 0xffff0000, v226
	v_add_f32_e32 v137, v137, v145
	v_add_f32_e32 v139, v139, v147
	v_add_f32_e32 v136, v136, v144
	v_add_f32_e32 v138, v138, v146
	v_add_f32_e32 v146, v132, v188
	v_add_f32_e32 v147, v133, v189
	v_mul_f32_e32 v132, v137, v137
	v_mul_f32_e32 v133, v139, v139
	v_fmac_f32_e32 v132, v136, v136
	v_fmac_f32_e32 v133, v138, v138
	v_and_b32_e32 v212, 0xffff0000, v227
	v_add_f32_e32 v132, v132, v133
	v_mul_f32_e32 v133, v147, v147
	v_cvt_pk_bf16_f32 v143, v210, v143
	v_lshlrev_b32_e32 v210, 16, v227
	v_add_f32_e32 v189, v135, v212
	v_fmac_f32_e32 v133, v146, v146
	v_add_f32_e32 v188, v134, v210
	v_add_f32_e32 v132, v133, v132
	v_mul_f32_e32 v133, v189, v189
	v_fmac_f32_e32 v133, v188, v188
	v_add_f32_e32 v132, v133, v132
	v_and_b32_e32 v134, 64, v216
	v_add_f32_e32 v133, v211, v132
	v_xor_b32_e32 v132, 16, v216
	v_add_u32_e32 v210, 64, v134
	v_cmp_lt_i32_e32 vcc, v132, v210
	v_lshl_add_u64 v[134:135], s[36:37], 0, v[208:209]
	v_lshl_add_u64 v[144:145], v[134:135], 0, v[186:187]
	v_cndmask_b32_e32 v132, v216, v132, vcc
	v_lshlrev_b32_e32 v132, 2, v132
	ds_bpermute_b32 v211, v132, v133
	global_store_dwordx4 v[144:145], v[140:143], off
	v_cvt_pk_bf16_f32 v136, v136, v137
	v_cvt_pk_bf16_f32 v137, v138, v139
	v_cvt_pk_bf16_f32 v138, v146, v147
	s_waitcnt lgkmcnt(0)
	v_add_f32_e32 v134, v133, v211
	v_xor_b32_e32 v133, 32, v216
	v_cmp_lt_i32_e32 vcc, v133, v210
	v_cvt_pk_bf16_f32 v139, v188, v189
	global_store_dwordx4 v[144:145], v[136:139], off offset:256
	s_nop 0
	v_cndmask_b32_e32 v133, v216, v133, vcc
	v_lshlrev_b32_e32 v133, 2, v133
	ds_bpermute_b32 v135, v133, v134
	s_and_saveexec_b64 s[0:1], s[8:9]
	s_cbranch_execz .LBB0_779
	v_lshl_add_u64 v[136:137], v[182:183], 2, s[4:5]
	s_waitcnt lgkmcnt(0)
	v_add_f32_e32 v134, v134, v135
	global_atomic_add_f32 v[136:137], v134, off

; __device__ __forceinline__ unsigned pk2(float lo, float hi) { return pg8::cvt_pk_bf16(lo, hi); }
; __device__ __forceinline__ void unpack8(const u32x4 w, float (&f)[8]) { f[0] = bflo(w.x); f[1] = bfhi(w.x); f[2] = bflo(w.y); f[3] = bfhi(w.y); f[4] = bflo(w.z); f[5] = bfhi(w.z); f[6] = bflo(w.w); f[7] = bfhi(w.w); }
;     __device__ __forceinline__ void operator()(const f32x4 (&acc)[2][2][4][2], const Unit& u, int wr, int wc, int fr, int fq) const {
;         const int row0 = u.pm * 256 + wr * 64 + fr, col0 = u.pn * 256 + wc * 32 + 8 * fq;
; #pragma unroll
;         for (int ai = 0; ai < 2; ++ai) {
;             u32x4 braw[4][2];
; #pragma unroll
;             for (int m = 0; m < 4; ++m)
; #pragma unroll
;                 for (int bj = 0; bj < 2; ++bj) braw[m][bj] = *(const u32x4*)(base + (size_t)(row0 + ai * 128 + m * 16) * DM + col0 + bj * 128);
;             __builtin_amdgcn_sched_barrier(0);
; #pragma unroll
;             for (int m = 0; m < 4; ++m) { const int row = row0 + ai * 128 + m * 16; const size_t off = (size_t)row * DM + col0; float sq = 0.f;
; #pragma unroll
;                 for (int bj = 0; bj < 2; ++bj) { float b[8]; unpack8(braw[m][bj], b);
;                     const f32x4 a0 = acc[ai][bj][m][0], a1 = acc[ai][bj][m][1];
;                     const f32x4 v0 = (f32x4){b[0] + a0[0], b[1] + a0[1], b[2] + a0[2], b[3] + a0[3]}, v1 = (f32x4){b[4] + a1[0], b[5] + a1[1], b[6] + a1[2], b[7] + a1[3]};
;                     sq += (v0[0] * v0[0] + v0[1] * v0[1]) + (v0[2] * v0[2] + v0[3] * v0[3]) + (v1[0] * v1[0] + v1[1] * v1[1]) + (v1[2] * v1[2] + v1[3] * v1[3]);
;                     if (Xf) { *(f32x4*)(Xf + off + bj * 128) = v0; *(f32x4*)(Xf + off + bj * 128 + 4) = v1; }
;                     if (XB) { u32x4 w; w.x = pk2(v0[0], v0[1]); w.y = pk2(v0[2], v0[3]); w.z = pk2(v1[0], v1[1]); w.w = pk2(v1[2], v1[3]); *(u32x4*)(XB + off + bj * 128) = w; } }
;                 if (ss) { sq += __shfl_xor(sq, 16); sq += __shfl_xor(sq, 32); if (fq == 0) atomicAdd(ss + row, sq); } } }
.LBB0_785:
	s_or_b64 exec, exec, s[0:1]
	v_add_u32_e32 v120, 0x80, v182
	v_ashrrev_i32_e32 v121, 31, v120
	v_add_u32_e32 v116, 0x90, v182
	v_lshlrev_b64 v[130:131], 11, v[120:121]
	v_ashrrev_i32_e32 v117, 31, v116
	v_add_u32_e32 v112, 0xa0, v182
	s_waitcnt lgkmcnt(0)
	v_lshl_add_u64 v[84:85], v[190:191], 0, v[130:131]
	v_lshlrev_b64 v[118:119], 11, v[116:117]
	v_ashrrev_i32_e32 v113, 31, v112
	v_add_u32_e32 v108, 0xb0, v182
	s_cmp_lg_u64 s[10:11], 0
	s_cbranch_scc0 .Lhz_g4_lds
	global_load_dwordx4 v[122:125], v[84:85], off
	global_load_dwordx4 v[126:129], v[84:85], off offset:256
	v_lshl_add_u64 v[84:85], v[190:191], 0, v[118:119]
	v_lshlrev_b64 v[114:115], 11, v[112:113]
	v_ashrrev_i32_e32 v109, 31, v108
	global_load_dwordx4 v[104:107], v[84:85], off
	global_load_dwordx4 v[100:103], v[84:85], off offset:256
	v_lshl_add_u64 v[84:85], v[190:191], 0, v[114:115]
	v_lshlrev_b64 v[110:111], 11, v[108:109]
	global_load_dwordx4 v[96:99], v[84:85], off
	global_load_dwordx4 v[92:95], v[84:85], off offset:256
	v_lshl_add_u64 v[84:85], v[190:191], 0, v[110:111]
	global_load_dwordx4 v[88:91], v[84:85], off
	s_nop 0
	global_load_dwordx4 v[84:87], v[84:85], off offset:256
	s_waitcnt vmcnt(0)
	s_branch .Lhz_g4_join
.Lhz_g4_lds:
	v_readfirstlane_b32 s98, v184
	s_lshr_b32 s98, s98, 6
	s_lshl_b32 s98, s98, 10
	v_and_b32_e32 v240, 63, v184
	v_lshl_add_u32 v240, v240, 4, s98
	v_add_u32_e32 v241, 0x10000, v240
	ds_read_b128 v[122:125], v240 offset:0
	ds_read_b128 v[126:129], v240 offset:8192
	v_lshl_add_u64 v[84:85], v[190:191], 0, v[118:119]
	v_lshlrev_b64 v[114:115], 11, v[112:113]
	v_ashrrev_i32_e32 v109, 31, v108
	ds_read_b128 v[104:107], v240 offset:16384
	ds_read_b128 v[100:103], v240 offset:24576
	v_lshl_add_u64 v[84:85], v[190:191], 0, v[114:115]
	v_lshlrev_b64 v[110:111], 11, v[108:109]
	ds_read_b128 v[96:99], v241 offset:0
	ds_read_b128 v[92:95], v241 offset:8192
	v_lshl_add_u64 v[84:85], v[190:191], 0, v[110:111]
	ds_read_b128 v[88:91], v241 offset:16384
	ds_read_b128 v[84:87], v241 offset:24576
	s_waitcnt lgkmcnt(0)
.Lhz_g4_join:
	s_nop 0
	v_lshlrev_b32_e32 v134, 16, v122
	v_and_b32_e32 v122, 0xffff0000, v122
	v_lshlrev_b32_e32 v135, 16, v123
	v_and_b32_e32 v123, 0xffff0000, v123
	v_lshlrev_b32_e32 v136, 16, v124
	v_and_b32_e32 v124, 0xffff0000, v124
	v_add_f32_e32 v81, v81, v122
	v_add_f32_e32 v83, v83, v123
	v_add_f32_e32 v80, v80, v134
	v_add_f32_e32 v82, v82, v135
	v_add_f32_e32 v122, v76, v136
	v_add_f32_e32 v123, v77, v124
	v_mul_f32_e32 v76, v81, v81
	v_mul_f32_e32 v77, v83, v83
	v_fmac_f32_e32 v76, v80, v80
	v_fmac_f32_e32 v77, v82, v82
	v_lshlrev_b32_e32 v137, 16, v125
	v_and_b32_e32 v125, 0xffff0000, v125
	v_add_f32_e32 v76, v76, v77
	v_mul_f32_e32 v77, v123, v123
	v_add_f32_e32 v79, v79, v125
	v_fmac_f32_e32 v77, v122, v122
	v_add_f32_e32 v124, v78, v137
	v_add_f32_e32 v76, v77, v76
	v_mul_f32_e32 v77, v79, v79
	v_fmac_f32_e32 v77, v124, v124
	v_add_f32_e32 v125, v77, v76
	v_cvt_pk_bf16_f32 v76, v80, v81
	v_cvt_pk_bf16_f32 v77, v82, v83
	s_nop 0
	v_and_b32_e32 v81, 0xffff0000, v126
	v_and_b32_e32 v83, 0xffff0000, v127
	v_cvt_pk_bf16_f32 v78, v122, v123
	v_lshlrev_b32_e32 v80, 16, v126
	v_lshlrev_b32_e32 v82, 16, v127
	v_lshlrev_b32_e32 v122, 16, v128
	v_and_b32_e32 v123, 0xffff0000, v128
	v_add_f32_e32 v73, v73, v81
	v_add_f32_e32 v81, v75, v83
	v_add_f32_e32 v72, v72, v80
	v_add_f32_e32 v80, v74, v82
	v_add_f32_e32 v82, v68, v122
	v_add_f32_e32 v83, v69, v123
	v_mul_f32_e32 v68, v73, v73
	v_mul_f32_e32 v69, v81, v81
	v_fmac_f32_e32 v68, v72, v72
	v_fmac_f32_e32 v69, v80, v80
	v_and_b32_e32 v126, 0xffff0000, v129
	v_add_f32_e32 v68, v68, v69
	v_mul_f32_e32 v69, v83, v83
	v_cvt_pk_bf16_f32 v79, v124, v79
	v_lshlrev_b32_e32 v124, 16, v129
	v_add_f32_e32 v123, v71, v126
	v_fmac_f32_e32 v69, v82, v82
	v_add_f32_e32 v122, v70, v124
	v_add_f32_e32 v68, v69, v68
	v_mul_f32_e32 v69, v123, v123
	v_fmac_f32_e32 v69, v122, v122
	v_add_f32_e32 v68, v69, v68
	v_add_f32_e32 v71, v125, v68
	ds_bpermute_b32 v124, v132, v71
	v_lshl_add_u64 v[68:69], s[36:37], 0, v[130:131]
	v_lshl_add_u64 v[74:75], v[180:181], 1, v[68:69]
	global_store_dwordx4 v[74:75], v[76:79], off
	v_cvt_pk_bf16_f32 v70, v72, v73
	s_waitcnt lgkmcnt(0)
	v_add_f32_e32 v68, v71, v124
	ds_bpermute_b32 v69, v133, v68
	v_cvt_pk_bf16_f32 v71, v80, v81
	v_cvt_pk_bf16_f32 v72, v82, v83
	v_cvt_pk_bf16_f32 v73, v122, v123
	global_store_dwordx4 v[74:75], v[70:73], off offset:256
	s_and_saveexec_b64 s[0:1], s[8:9]
	s_cbranch_execz .LBB0_787
	v_lshl_add_u64 v[70:71], v[120:121], 2, s[4:5]
	s_waitcnt lgkmcnt(0)
	v_add_f32_e32 v68, v68, v69
	global_atomic_add_f32 v[70:71], v68, off
; __device__ __forceinline__ unsigned pk2(float lo, float hi) { return pg8::cvt_pk_bf16(lo, hi); }
; __device__ __forceinline__ void unpack8(const u32x4 w, float (&f)[8]) { f[0] = bflo(w.x); f[1] = bfhi(w.x); f[2] = bflo(w.y); f[3] = bfhi(w.y); f[4] = bflo(w.z); f[5] = bfhi(w.z); f[6] = bflo(w.w); f[7] = bfhi(w.w); }
;     __device__ __forceinline__ void operator()(const f32x4 (&acc)[2][2][4][2], const Unit& u, int wr, int wc, int fr, int fq) const {
;         const int row0 = u.pm * 256 + wr * 64 + fr, col0 = u.pn * 256 + wc * 32 + 8 * fq;
; #pragma unroll
;         for (int ai = 0; ai < 2; ++ai) {
;             u32x4 braw[4][2];
; #pragma unroll
;             for (int m = 0; m < 4; ++m)
; #pragma unroll
;                 for (int bj = 0; bj < 2; ++bj) braw[m][bj] = *(const u32x4*)(base + (size_t)(row0 + ai * 128 + m * 16) * DM + col0 + bj * 128);
;             __builtin_amdgcn_sched_barrier(0);
; #pragma unroll
;             for (int m = 0; m < 4; ++m) { const int row = row0 + ai * 128 + m * 16; const size_t off = (size_t)row * DM + col0; float sq = 0.f;
; #pragma unroll
;                 for (int bj = 0; bj < 2; ++bj) { float b[8]; unpack8(braw[m][bj], b);
;                     const f32x4 a0 = acc[ai][bj][m][0], a1 = acc[ai][bj][m][1];
;                     const f32x4 v0 = (f32x4){b[0] + a0[0], b[1] + a0[1], b[2] + a0[2], b[3] + a0[3]}, v1 = (f32x4){b[4] + a1[0], b[5] + a1[1], b[6] + a1[2], b[7] + a1[3]};
;                     sq += (v0[0] * v0[0] + v0[1] * v0[1]) + (v0[2] * v0[2] + v0[3] * v0[3]) + (v1[0] * v1[0] + v1[1] * v1[1]) + (v1[2] * v1[2] + v1[3] * v1[3]);
;                     if (Xf) { *(f32x4*)(Xf + off + bj * 128) = v0; *(f32x4*)(Xf + off + bj * 128 + 4) = v1; }
;                     if (XB) { u32x4 w; w.x = pk2(v0[0], v0[1]); w.y = pk2(v0[2], v0[3]); w.z = pk2(v1[0], v1[1]); w.w = pk2(v1[2], v1[3]); *(u32x4*)(XB + off + bj * 128) = w; } }
;                 if (ss) { sq += __shfl_xor(sq, 16); sq += __shfl_xor(sq, 32); if (fq == 0) atomicAdd(ss + row, sq); } } }
.LBB0_787:
	s_or_b64 exec, exec, s[0:1]
	s_waitcnt lgkmcnt(0)
	v_and_b32_e32 v69, 0xffff0000, v104
	v_and_b32_e32 v71, 0xffff0000, v105
	v_lshlrev_b32_e32 v68, 16, v104
	v_lshlrev_b32_e32 v70, 16, v105
	v_lshlrev_b32_e32 v72, 16, v106
	v_and_b32_e32 v73, 0xffff0000, v106
	v_add_f32_e32 v65, v65, v69
	v_add_f32_e32 v67, v67, v71
	v_add_f32_e32 v64, v64, v68
	v_add_f32_e32 v66, v66, v70
	v_add_f32_e32 v68, v60, v72
	v_add_f32_e32 v69, v61, v73
	v_mul_f32_e32 v60, v65, v65
	v_mul_f32_e32 v61, v67, v67
	v_fmac_f32_e32 v60, v64, v64
	v_fmac_f32_e32 v61, v66, v66
	v_and_b32_e32 v75, 0xffff0000, v107
	v_add_f32_e32 v60, v60, v61
	v_mul_f32_e32 v61, v69, v69
	v_lshlrev_b32_e32 v74, 16, v107
	v_add_f32_e32 v63, v63, v75
	v_fmac_f32_e32 v61, v68, v68
	v_add_f32_e32 v70, v62, v74
	v_add_f32_e32 v60, v61, v60
	v_mul_f32_e32 v61, v63, v63
	v_fmac_f32_e32 v61, v70, v70
	v_add_f32_e32 v71, v61, v60
	v_cvt_pk_bf16_f32 v60, v64, v65
	v_cvt_pk_bf16_f32 v61, v66, v67
	s_nop 0
	v_and_b32_e32 v65, 0xffff0000, v100
	v_and_b32_e32 v67, 0xffff0000, v101
	v_cvt_pk_bf16_f32 v62, v68, v69
	v_lshlrev_b32_e32 v64, 16, v100
	v_lshlrev_b32_e32 v66, 16, v101
	v_lshlrev_b32_e32 v68, 16, v102
	v_and_b32_e32 v69, 0xffff0000, v102
	v_add_f32_e32 v57, v57, v65
	v_add_f32_e32 v65, v59, v67
	v_add_f32_e32 v56, v56, v64
	v_add_f32_e32 v64, v58, v66
	v_add_f32_e32 v66, v52, v68
	v_add_f32_e32 v67, v53, v69
	v_mul_f32_e32 v52, v57, v57
	v_mul_f32_e32 v53, v65, v65
	v_fmac_f32_e32 v52, v56, v56
	v_fmac_f32_e32 v53, v64, v64
	v_and_b32_e32 v72, 0xffff0000, v103
	v_add_f32_e32 v52, v52, v53
	v_mul_f32_e32 v53, v67, v67
	v_cvt_pk_bf16_f32 v63, v70, v63
	v_lshlrev_b32_e32 v70, 16, v103
	v_add_f32_e32 v69, v55, v72
	v_fmac_f32_e32 v53, v66, v66
	v_add_f32_e32 v68, v54, v70
	v_add_f32_e32 v52, v53, v52
	v_mul_f32_e32 v53, v69, v69
	v_fmac_f32_e32 v53, v68, v68
	v_add_f32_e32 v52, v53, v52
	v_add_f32_e32 v55, v71, v52
	ds_bpermute_b32 v70, v132, v55
	v_lshl_add_u64 v[52:53], s[36:37], 0, v[118:119]
	v_lshl_add_u64 v[58:59], v[180:181], 1, v[52:53]
	global_store_dwordx4 v[58:59], v[60:63], off
	v_cvt_pk_bf16_f32 v54, v56, v57
	s_waitcnt lgkmcnt(0)
	v_add_f32_e32 v52, v55, v70
	ds_bpermute_b32 v53, v133, v52
	v_cvt_pk_bf16_f32 v55, v64, v65
	v_cvt_pk_bf16_f32 v56, v66, v67
	v_cvt_pk_bf16_f32 v57, v68, v69
	global_store_dwordx4 v[58:59], v[54:57], off offset:256
	s_and_saveexec_b64 s[0:1], s[8:9]
	s_cbranch_execz .LBB0_789
	v_lshl_add_u64 v[54:55], v[116:117], 2, s[4:5]
	s_waitcnt lgkmcnt(0)
	v_add_f32_e32 v52, v52, v53
	global_atomic_add_f32 v[54:55], v52, off
; __device__ __forceinline__ unsigned pk2(float lo, float hi) { return pg8::cvt_pk_bf16(lo, hi); }
; __device__ __forceinline__ void unpack8(const u32x4 w, float (&f)[8]) { f[0] = bflo(w.x); f[1] = bfhi(w.x); f[2] = bflo(w.y); f[3] = bfhi(w.y); f[4] = bflo(w.z); f[5] = bfhi(w.z); f[6] = bflo(w.w); f[7] = bfhi(w.w); }
;     __device__ __forceinline__ void operator()(const f32x4 (&acc)[2][2][4][2], const Unit& u, int wr, int wc, int fr, int fq) const {
;         const int row0 = u.pm * 256 + wr * 64 + fr, col0 = u.pn * 256 + wc * 32 + 8 * fq;
; #pragma unroll
;         for (int ai = 0; ai < 2; ++ai) {
;             u32x4 braw[4][2];
; #pragma unroll
;             for (int m = 0; m < 4; ++m)
; #pragma unroll
;                 for (int bj = 0; bj < 2; ++bj) braw[m][bj] = *(const u32x4*)(base + (size_t)(row0 + ai * 128 + m * 16) * DM + col0 + bj * 128);
;             __builtin_amdgcn_sched_barrier(0);
; #pragma unroll
;             for (int m = 0; m < 4; ++m) { const int row = row0 + ai * 128 + m * 16; const size_t off = (size_t)row * DM + col0; float sq = 0.f;
; #pragma unroll
;                 for (int bj = 0; bj < 2; ++bj) { float b[8]; unpack8(braw[m][bj], b);
;                     const f32x4 a0 = acc[ai][bj][m][0], a1 = acc[ai][bj][m][1];
;                     const f32x4 v0 = (f32x4){b[0] + a0[0], b[1] + a0[1], b[2] + a0[2], b[3] + a0[3]}, v1 = (f32x4){b[4] + a1[0], b[5] + a1[1], b[6] + a1[2], b[7] + a1[3]};
;                     sq += (v0[0] * v0[0] + v0[1] * v0[1]) + (v0[2] * v0[2] + v0[3] * v0[3]) + (v1[0] * v1[0] + v1[1] * v1[1]) + (v1[2] * v1[2] + v1[3] * v1[3]);
;                     if (Xf) { *(f32x4*)(Xf + off + bj * 128) = v0; *(f32x4*)(Xf + off + bj * 128 + 4) = v1; }
;                     if (XB) { u32x4 w; w.x = pk2(v0[0], v0[1]); w.y = pk2(v0[2], v0[3]); w.z = pk2(v1[0], v1[1]); w.w = pk2(v1[2], v1[3]); *(u32x4*)(XB + off + bj * 128) = w; } }
;                 if (ss) { sq += __shfl_xor(sq, 16); sq += __shfl_xor(sq, 32); if (fq == 0) atomicAdd(ss + row, sq); } } }
.LBB0_789:
	s_or_b64 exec, exec, s[0:1]
	s_waitcnt lgkmcnt(0)
	v_and_b32_e32 v53, 0xffff0000, v96
	v_and_b32_e32 v55, 0xffff0000, v97
	v_lshlrev_b32_e32 v52, 16, v96
	v_lshlrev_b32_e32 v54, 16, v97
	v_lshlrev_b32_e32 v56, 16, v98
	v_and_b32_e32 v57, 0xffff0000, v98
	v_add_f32_e32 v49, v49, v53
	v_add_f32_e32 v51, v51, v55
	v_add_f32_e32 v48, v48, v52
	v_add_f32_e32 v50, v50, v54
	v_add_f32_e32 v52, v44, v56
	v_add_f32_e32 v53, v45, v57
	v_mul_f32_e32 v44, v49, v49
	v_mul_f32_e32 v45, v51, v51
	v_fmac_f32_e32 v44, v48, v48
	v_fmac_f32_e32 v45, v50, v50
	v_and_b32_e32 v59, 0xffff0000, v99
	v_add_f32_e32 v44, v44, v45
	v_mul_f32_e32 v45, v53, v53
	v_lshlrev_b32_e32 v58, 16, v99
	v_add_f32_e32 v47, v47, v59
	v_fmac_f32_e32 v45, v52, v52
	v_add_f32_e32 v54, v46, v58
	v_add_f32_e32 v44, v45, v44
	v_mul_f32_e32 v45, v47, v47
	v_fmac_f32_e32 v45, v54, v54
	v_add_f32_e32 v55, v45, v44
	v_cvt_pk_bf16_f32 v44, v48, v49
	v_cvt_pk_bf16_f32 v45, v50, v51
	s_nop 0
	v_and_b32_e32 v49, 0xffff0000, v92
	v_and_b32_e32 v51, 0xffff0000, v93
	v_cvt_pk_bf16_f32 v46, v52, v53
	v_lshlrev_b32_e32 v48, 16, v92
	v_lshlrev_b32_e32 v50, 16, v93
	v_lshlrev_b32_e32 v52, 16, v94
	v_and_b32_e32 v53, 0xffff0000, v94
	v_add_f32_e32 v41, v41, v49
	v_add_f32_e32 v49, v43, v51
	v_add_f32_e32 v40, v40, v48
	v_add_f32_e32 v48, v42, v50
	v_add_f32_e32 v50, v36, v52
	v_add_f32_e32 v51, v37, v53
	v_mul_f32_e32 v36, v41, v41
	v_mul_f32_e32 v37, v49, v49
	v_fmac_f32_e32 v36, v40, v40
	v_fmac_f32_e32 v37, v48, v48
	v_and_b32_e32 v56, 0xffff0000, v95
	v_add_f32_e32 v36, v36, v37
	v_mul_f32_e32 v37, v51, v51
	v_cvt_pk_bf16_f32 v47, v54, v47
	v_lshlrev_b32_e32 v54, 16, v95
	v_add_f32_e32 v53, v39, v56
	v_fmac_f32_e32 v37, v50, v50
	v_add_f32_e32 v52, v38, v54
	v_add_f32_e32 v36, v37, v36
	v_mul_f32_e32 v37, v53, v53
	v_fmac_f32_e32 v37, v52, v52
	v_add_f32_e32 v36, v37, v36
	v_add_f32_e32 v39, v55, v36
	ds_bpermute_b32 v54, v132, v39
	v_lshl_add_u64 v[36:37], s[36:37], 0, v[114:115]
	v_lshl_add_u64 v[42:43], v[180:181], 1, v[36:37]
	global_store_dwordx4 v[42:43], v[44:47], off
	v_cvt_pk_bf16_f32 v38, v40, v41
	s_waitcnt lgkmcnt(0)
	v_add_f32_e32 v36, v39, v54
	ds_bpermute_b32 v37, v133, v36
	v_cvt_pk_bf16_f32 v39, v48, v49
	v_cvt_pk_bf16_f32 v40, v50, v51
	v_cvt_pk_bf16_f32 v41, v52, v53
	global_store_dwordx4 v[42:43], v[38:41], off offset:256
	s_and_saveexec_b64 s[0:1], s[8:9]
	s_cbranch_execz .LBB0_791
	v_lshl_add_u64 v[38:39], v[112:113], 2, s[4:5]
	s_waitcnt lgkmcnt(0)
	v_add_f32_e32 v36, v36, v37
	global_atomic_add_f32 v[38:39], v36, off
.LBB0_791:
	s_or_b64 exec, exec, s[0:1]
	s_waitcnt lgkmcnt(0)
	v_and_b32_e32 v37, 0xffff0000, v88
	v_and_b32_e32 v39, 0xffff0000, v89
	v_lshlrev_b32_e32 v36, 16, v88
	v_lshlrev_b32_e32 v38, 16, v89
	v_lshlrev_b32_e32 v40, 16, v90
	v_and_b32_e32 v41, 0xffff0000, v90
	v_add_f32_e32 v33, v33, v37
	v_add_f32_e32 v35, v35, v39
	v_add_f32_e32 v32, v32, v36
	v_add_f32_e32 v34, v34, v38
	v_add_f32_e32 v36, v28, v40
	v_add_f32_e32 v37, v29, v41
	v_mul_f32_e32 v28, v33, v33
	v_mul_f32_e32 v29, v35, v35
	v_fmac_f32_e32 v28, v32, v32
	v_fmac_f32_e32 v29, v34, v34
	v_and_b32_e32 v43, 0xffff0000, v91
	v_add_f32_e32 v28, v28, v29
	v_mul_f32_e32 v29, v37, v37
	v_lshlrev_b32_e32 v42, 16, v91
	v_add_f32_e32 v31, v31, v43
	v_fmac_f32_e32 v29, v36, v36
	v_add_f32_e32 v38, v30, v42
	v_add_f32_e32 v28, v29, v28
	v_mul_f32_e32 v29, v31, v31
	v_fmac_f32_e32 v29, v38, v38
	v_add_f32_e32 v39, v29, v28
	v_cvt_pk_bf16_f32 v28, v32, v33
	v_cvt_pk_bf16_f32 v29, v34, v35
	s_nop 0
	v_and_b32_e32 v33, 0xffff0000, v84
	v_and_b32_e32 v35, 0xffff0000, v85
	v_cvt_pk_bf16_f32 v30, v36, v37
	v_lshlrev_b32_e32 v32, 16, v84
	v_lshlrev_b32_e32 v34, 16, v85
	v_lshlrev_b32_e32 v36, 16, v86
	v_and_b32_e32 v37, 0xffff0000, v86
	v_add_f32_e32 v25, v25, v33
	v_add_f32_e32 v33, v27, v35
	v_add_f32_e32 v24, v24, v32
	v_add_f32_e32 v32, v26, v34
	v_add_f32_e32 v34, v20, v36
	v_add_f32_e32 v35, v21, v37
	v_mul_f32_e32 v20, v25, v25
	v_mul_f32_e32 v21, v33, v33
	v_fmac_f32_e32 v20, v24, v24
	v_fmac_f32_e32 v21, v32, v32
	v_and_b32_e32 v40, 0xffff0000, v87
	v_add_f32_e32 v20, v20, v21
	v_mul_f32_e32 v21, v35, v35
	v_cvt_pk_bf16_f32 v31, v38, v31
	v_lshlrev_b32_e32 v38, 16, v87
	v_add_f32_e32 v37, v23, v40
	v_fmac_f32_e32 v21, v34, v34
	v_add_f32_e32 v36, v22, v38
	v_add_f32_e32 v20, v21, v20
	v_mul_f32_e32 v21, v37, v37
	v_fmac_f32_e32 v21, v36, v36
	v_add_f32_e32 v20, v21, v20
	v_add_f32_e32 v23, v39, v20
	ds_bpermute_b32 v38, v132, v23
	v_lshl_add_u64 v[20:21], s[36:37], 0, v[110:111]
	v_lshl_add_u64 v[26:27], v[180:181], 1, v[20:21]
	global_store_dwordx4 v[26:27], v[28:31], off
	v_cvt_pk_bf16_f32 v22, v24, v25
	s_waitcnt lgkmcnt(0)
	v_add_f32_e32 v20, v23, v38
	ds_bpermute_b32 v21, v133, v20
	v_cvt_pk_bf16_f32 v23, v32, v33
	v_cvt_pk_bf16_f32 v24, v34, v35
	v_cvt_pk_bf16_f32 v25, v36, v37
	global_store_dwordx4 v[26:27], v[22:25], off offset:256
	s_and_saveexec_b64 s[0:1], s[8:9]
	s_cbranch_execz .LBB0_793
	v_lshl_add_u64 v[22:23], v[108:109], 2, s[4:5]
	s_waitcnt lgkmcnt(0)
	v_add_f32_e32 v20, v20, v21
	global_atomic_add_f32 v[22:23], v20, off
